# counted waits at the heads of the P2 chunk-state and P4 retention item loops: vmcnt(0) -> vmcnt(8) (previous item's 8 result stores may stay in flight), preheader keeps vmcnt(0); on top of v111
# speedup vs baseline: 1.0061x; 1.0022x over previous
.LBB0_414:
	s_cmpk_lt_i32 s2, 0x400
	s_cbranch_scc0 .LBB0_419
	s_ashr_i32 s4, s2, 8
	s_ashr_i32 s5, s4, 31
	s_lshl_b32 s6, s2, 17
	s_lshl_b64 s[4:5], s[4:5], 23
	s_and_b32 s6, s6, 0x7e0000
	s_or_b32 s4, s4, s6
	v_readlane_b32 s6, v254, 39
	s_add_u32 s6, s6, s4
	v_readlane_b32 s7, v254, 40
	s_addc_u32 s7, s7, s5
	s_lshl_b32 s8, s2, 2
	s_and_b32 s8, s8, 0x300
	s_add_u32 s6, s6, s8
	s_addc_u32 s7, s7, 0
	v_mov_b32_e32 v33, 0
	v_lshl_add_u64 v[0:1], s[6:7], 0, v[32:33]
	v_lshlrev_b32_e32 v12, 5, v220
	s_add_u32 s4, s77, s4
	v_readlane_b32 s6, v254, 42
	v_add_u32_e32 v4, 0x4000, v12
	v_add_u32_e32 v12, 0xc000, v12
	s_addc_u32 s5, s6, s5
	v_and_b32_e32 v4, 0xfe00, v4
	v_or_b32_e32 v60, 0x8000, v30
	v_and_b32_e32 v12, 0x1fe00, v12
	s_add_u32 s4, s4, s8
	v_mov_b32_e32 v35, v33
	v_lshlrev_b32_e32 v4, 1, v4
	v_mov_b32_e32 v5, v33
	v_lshlrev_b32_e32 v8, 1, v60
	v_mov_b32_e32 v9, v33
	v_lshlrev_b32_e32 v12, 1, v12
	v_mov_b32_e32 v13, v33
	s_addc_u32 s5, s5, 0
	v_lshl_add_u64 v[2:3], v[0:1], 0, v[34:35]
	v_lshl_add_u64 v[6:7], v[0:1], 0, v[4:5]
	v_lshl_add_u64 v[10:11], v[0:1], 0, v[8:9]
	v_lshl_add_u64 v[14:15], v[0:1], 0, v[12:13]
	v_lshl_add_u64 v[0:1], s[4:5], 0, v[32:33]
	v_lshl_add_u64 v[16:17], v[0:1], 0, v[34:35]
	v_lshl_add_u64 v[20:21], v[0:1], 0, v[4:5]
	v_lshl_add_u64 v[24:25], v[0:1], 0, v[8:9]
	v_lshl_add_u64 v[28:29], v[0:1], 0, v[12:13]
	global_load_dwordx4 v[0:3], v[2:3], off
	s_nop 0
	global_load_dwordx4 v[4:7], v[6:7], off
	s_nop 0
	global_load_dwordx4 v[8:11], v[10:11], off
	s_nop 0
	global_load_dwordx4 v[12:15], v[14:15], off
	s_nop 0
	global_load_dwordx4 v[16:19], v[16:17], off
	s_nop 0
	global_load_dwordx4 v[20:23], v[20:21], off
	s_nop 0
	global_load_dwordx4 v[24:27], v[24:25], off
	s_nop 0
	global_load_dwordx4 v[28:31], v[28:29], off
	v_xor_b32_e32 v35, 0x7f, v42
	v_cvt_f32_ubyte0_e32 v49, v35
	v_xor_b32_e32 v35, 0x7f, v47
	v_cvt_f32_ubyte0_e32 v47, v35
	v_xor_b32_e32 v35, 63, v42
	v_cvt_f32_ubyte0_e32 v50, v35
	v_sub_u32_e32 v35, 0x7f, v43
	v_cvt_f32_i32_e32 v51, v35
	v_lshrrev_b32_e32 v35, 1, v220
	v_lshlrev_b32_e32 v39, 2, v220
	s_cmp_lg_u32 0, -1
	v_and_b32_e32 v35, 24, v35
	v_and_or_b32 v39, v39, 12, s3
	s_cselect_b32 s3, 0, 0
	v_and_b32_e32 v41, 24, v41
	v_and_or_b32 v37, v48, 3, v35
	s_add_i32 s4, s3, 0x8800
	v_add_u32_e32 v41, s3, v41
	s_movk_i32 s3, 0x110
	v_mov_b32_e32 v42, 0x2200
	v_lshl_add_u32 v39, v39, 1, s4
	v_mad_u32_u24 v42, v37, s3, v42
	v_add_u32_e32 v53, v39, v42
	v_add_u32_e32 v54, v42, v41
	v_mov_b32_e32 v42, 0x4400
	v_mad_u32_u24 v42, v37, s3, v42
	v_add_u32_e32 v55, v39, v42
	v_add_u32_e32 v56, v42, v41
	v_mov_b32_e32 v42, 0x6600
	v_mad_u32_u24 v48, v37, s3, v39
	v_mad_u32_u24 v52, v37, s3, v41
	v_mad_u32_u24 v37, v37, s3, v42
	s_add_i32 s3, s2, s92
	s_lshl_b32 s8, s3, 1
	s_lshl_b32 s10, s3, 16
	s_ashr_i32 s3, s2, 31
	s_lshl_b64 s[4:5], s[2:3], 15
	v_or_b32_e32 v42, s4, v35
	v_lshlrev_b32_e32 v35, 7, v40
	v_lshl_or_b32 v40, s94, 11, v35
	v_add_u32_e32 v58, v37, v41
	v_mov_b32_e32 v43, s5
	v_ashrrev_i32_e32 v41, 31, v40
	v_lshl_add_u64 v[40:41], v[40:41], 1, v[42:43]
	v_lshl_add_u64 v[40:41], s[88:89], 0, v[40:41]
	s_mov_b64 s[4:5], 0x1b800080
	v_lshl_add_u64 v[40:41], v[40:41], 0, s[4:5]
	s_ashr_i32 s5, s92, 31
	s_mov_b32 s4, s92
	v_add_u32_e32 v57, v39, v37
	s_lshl_b32 s9, s92, 1
	s_lshl_b32 s11, s92, 16
	s_lshl_b64 s[4:5], s[4:5], 15
	v_mov_b32_e32 v59, 0xc0a00000
	s_mov_b32 s3, 0xc2fc0000
	s_mov_b32 s12, 0x800000
	v_lshlrev_b32_e32 v42, 1, v60
	v_mov_b32_e32 v60, 0x42800000
	v_mov_b32_e32 v61, 0x42000000
	v_not_b32_e32 v62, 63
	s_mov_b32 s13, s2
	s_waitcnt vmcnt(0)
	s_branch .LBB0_417

.LBB0_417:
	s_bfe_u32 s6, s13, 0x20006
	v_cvt_f32_ubyte0_e32 v35, s6
	v_fmamk_f32 v35, v35, 0xbfaaaaab, v59
	v_cmp_gt_f32_e32 vcc, s3, v35
	s_and_b64 s[6:7], vcc, exec
	s_cselect_b32 s6, 0xffffffc0, 0
	v_cndmask_b32_e32 v37, 0, v60, vcc
	v_add_f32_e32 v35, v35, v37
	v_exp_f32_e32 v35, v35
	s_waitcnt vmcnt(8)
	v_lshlrev_b32_e32 v64, 16, v16
	v_and_b32_e32 v65, 0xffff0000, v16
	v_lshlrev_b32_e32 v66, 16, v17
	v_ldexp_f32 v35, v35, s6
	v_sub_f32_e32 v35, 1.0, v35
	v_cmp_gt_f32_e32 vcc, s12, v35
	s_and_b64 s[6:7], vcc, exec
	s_cselect_b32 s6, 32, 0
	v_ldexp_f32 v35, v35, s6
	v_log_f32_e32 v35, v35
	v_cndmask_b32_e32 v37, 0, v61, vcc
	v_and_b32_e32 v67, 0xffff0000, v17
	v_lshlrev_b32_e32 v70, 16, v19
	v_sub_f32_e32 v35, v35, v37
	v_mul_f32_e32 v37, v35, v49
	v_cmp_gt_f32_e32 vcc, s3, v37
	v_and_b32_e32 v71, 0xffff0000, v19
	ds_write_b128 v44, v[0:3]
	ds_write_b128 v45, v[4:7]
	v_cndmask_b32_e32 v37, 0, v60, vcc
	v_fmac_f32_e32 v37, v35, v49
	v_exp_f32_e32 v37, v37
	v_cndmask_b32_e32 v39, 0, v62, vcc
	ds_write_b128 v44, v[8:11] offset:17408
	ds_write_b128 v46, v[12:15]
	s_add_i32 s13, s13, s92
	v_ldexp_f32 v68, v37, v39
	v_mul_f32_e32 v37, v35, v47
	v_cmp_gt_f32_e32 vcc, s3, v37
	v_pk_mul_f32 v[64:65], v[68:69], v[64:65] op_sel_hi:[0,1]
	v_pk_mul_f32 v[66:67], v[68:69], v[66:67] op_sel_hi:[0,1]
	v_cndmask_b32_e32 v37, 0, v60, vcc
	v_fmac_f32_e32 v37, v35, v47
	v_exp_f32_e32 v37, v37
	v_cvt_pk_bf16_f32 v64, v64, v65
	v_cvt_pk_bf16_f32 v65, v66, v67
	v_lshlrev_b32_e32 v66, 16, v18
	v_and_b32_e32 v67, 0xffff0000, v18
	v_pk_mul_f32 v[66:67], v[68:69], v[66:67] op_sel_hi:[0,1]
	v_pk_mul_f32 v[68:69], v[68:69], v[70:71] op_sel_hi:[0,1]
	v_cndmask_b32_e32 v39, 0, v62, vcc
	v_cvt_pk_bf16_f32 v66, v66, v67
	v_cvt_pk_bf16_f32 v67, v68, v69
	v_ldexp_f32 v68, v37, v39
	v_mul_f32_e32 v37, v35, v50
	v_cmp_gt_f32_e32 vcc, s3, v37
	ds_write_b128 v44, v[64:67] offset:34816
	v_lshlrev_b32_e32 v64, 16, v20
	v_cndmask_b32_e32 v37, 0, v60, vcc
	v_fmac_f32_e32 v37, v35, v50
	v_and_b32_e32 v65, 0xffff0000, v20
	v_lshlrev_b32_e32 v66, 16, v21
	v_and_b32_e32 v67, 0xffff0000, v21
	v_exp_f32_e32 v37, v37
	v_pk_mul_f32 v[64:65], v[68:69], v[64:65] op_sel_hi:[0,1]
	v_pk_mul_f32 v[66:67], v[68:69], v[66:67] op_sel_hi:[0,1]
	v_cvt_pk_bf16_f32 v64, v64, v65
	v_cvt_pk_bf16_f32 v65, v66, v67
	v_lshlrev_b32_e32 v66, 16, v22
	v_and_b32_e32 v67, 0xffff0000, v22
	v_lshlrev_b32_e32 v70, 16, v23
	v_and_b32_e32 v71, 0xffff0000, v23
	v_pk_mul_f32 v[66:67], v[68:69], v[66:67] op_sel_hi:[0,1]
	v_pk_mul_f32 v[68:69], v[68:69], v[70:71] op_sel_hi:[0,1]
	v_cndmask_b32_e32 v39, 0, v62, vcc
	v_cvt_pk_bf16_f32 v66, v66, v67
	v_cvt_pk_bf16_f32 v67, v68, v69
	v_ldexp_f32 v68, v37, v39
	v_mul_f32_e32 v37, v35, v51
	v_cmp_gt_f32_e32 vcc, s3, v37
	ds_write_b128 v45, v[64:67] offset:34816
	v_lshlrev_b32_e32 v64, 16, v24
	v_cndmask_b32_e32 v37, 0, v60, vcc
	v_and_b32_e32 v65, 0xffff0000, v24
	v_lshlrev_b32_e32 v66, 16, v25
	v_and_b32_e32 v67, 0xffff0000, v25
	v_fmac_f32_e32 v37, v35, v51
	v_pk_mul_f32 v[64:65], v[68:69], v[64:65] op_sel_hi:[0,1]
	v_pk_mul_f32 v[66:67], v[68:69], v[66:67] op_sel_hi:[0,1]
	v_exp_f32_e32 v35, v37
	v_cvt_pk_bf16_f32 v64, v64, v65
	v_cvt_pk_bf16_f32 v65, v66, v67
	v_lshlrev_b32_e32 v66, 16, v26
	v_and_b32_e32 v67, 0xffff0000, v26
	v_lshlrev_b32_e32 v70, 16, v27
	v_and_b32_e32 v71, 0xffff0000, v27
	v_pk_mul_f32 v[66:67], v[68:69], v[66:67] op_sel_hi:[0,1]
	v_pk_mul_f32 v[68:69], v[68:69], v[70:71] op_sel_hi:[0,1]
	v_cvt_pk_bf16_f32 v66, v66, v67
	v_cvt_pk_bf16_f32 v67, v68, v69
	v_cndmask_b32_e32 v37, 0, v62, vcc
	ds_write_b128 v44, v[64:67] offset:52224
	v_ldexp_f32 v68, v35, v37
	v_lshlrev_b32_e32 v64, 16, v28
	v_and_b32_e32 v65, 0xffff0000, v28
	v_lshlrev_b32_e32 v66, 16, v29
	v_and_b32_e32 v67, 0xffff0000, v29
	v_pk_mul_f32 v[64:65], v[68:69], v[64:65] op_sel_hi:[0,1]
	v_pk_mul_f32 v[66:67], v[68:69], v[66:67] op_sel_hi:[0,1]
	v_cvt_pk_bf16_f32 v64, v64, v65
	v_cvt_pk_bf16_f32 v65, v66, v67
	v_lshlrev_b32_e32 v66, 16, v30
	v_and_b32_e32 v67, 0xffff0000, v30
	v_lshlrev_b32_e32 v70, 16, v31
	v_and_b32_e32 v71, 0xffff0000, v31
	s_cmpk_gt_i32 s13, 0x3ff
	v_pk_mul_f32 v[66:67], v[68:69], v[66:67] op_sel_hi:[0,1]
	v_pk_mul_f32 v[68:69], v[68:69], v[70:71] op_sel_hi:[0,1]
	s_cselect_b64 s[6:7], -1, 0
	v_cvt_pk_bf16_f32 v66, v66, v67
	v_cvt_pk_bf16_f32 v67, v68, v69
	s_and_b64 vcc, exec, s[6:7]
	ds_write_b128 v46, v[64:67] offset:34816
	s_waitcnt lgkmcnt(0)
	s_barrier
	s_cbranch_vccnz .LBB0_416
	s_ashr_i32 s18, s13, 8
	s_ashr_i32 s19, s18, 31
	s_and_b32 s20, s10, 0x3f0000
	s_lshl_b64 s[18:19], s[18:19], 23
	s_lshl_b32 s20, s20, 1
	s_or_b32 s18, s18, s20
	v_readlane_b32 s20, v254, 39
	s_add_u32 s20, s20, s18
	v_readlane_b32 s21, v254, 40
	s_addc_u32 s21, s21, s19
	s_and_b32 s22, s8, 0x180
	s_lshl_b32 s22, s22, 1
	s_add_u32 s20, s20, s22
	s_addc_u32 s21, s21, 0
	v_lshl_add_u64 v[8:9], s[20:21], 0, v[32:33]
	s_add_u32 s18, s77, s18
	v_readlane_b32 s20, v254, 42
	s_addc_u32 s19, s20, s19
	s_add_u32 s18, s18, s22
	s_addc_u32 s19, s19, 0
	v_mov_b32_e32 v35, v33
	v_mov_b32_e32 v37, v33
	v_mov_b32_e32 v43, v33
	v_mov_b32_e32 v39, v33
	v_lshl_add_u64 v[24:25], s[18:19], 0, v[32:33]
	v_lshl_add_u64 v[0:1], v[8:9], 0, v[34:35]
	v_lshl_add_u64 v[4:5], v[8:9], 0, v[36:37]
	v_lshl_add_u64 v[10:11], v[8:9], 0, v[42:43]
	v_lshl_add_u64 v[12:13], v[8:9], 0, v[38:39]
	v_lshl_add_u64 v[16:17], v[24:25], 0, v[34:35]
	v_lshl_add_u64 v[20:21], v[24:25], 0, v[36:37]
	v_lshl_add_u64 v[26:27], v[24:25], 0, v[42:43]
	v_lshl_add_u64 v[28:29], v[24:25], 0, v[38:39]
	global_load_dwordx4 v[0:3], v[0:1], off
	s_nop 0
	global_load_dwordx4 v[4:7], v[4:5], off
	s_nop 0
	global_load_dwordx4 v[8:11], v[10:11], off
	s_nop 0
	global_load_dwordx4 v[12:15], v[12:13], off
	s_nop 0
	global_load_dwordx4 v[16:19], v[16:17], off
	s_nop 0
	global_load_dwordx4 v[20:23], v[20:21], off
	s_nop 0
	global_load_dwordx4 v[24:27], v[26:27], off
	s_nop 0
	global_load_dwordx4 v[28:31], v[28:29], off
	s_branch .LBB0_416

.LBB0_575:
	s_cmpk_gt_i32 s2, 0x3ff
	s_cbranch_scc1 .LBB0_581
	v_writelane_b32 v254, s56, 47
	s_mov_b64 s[68:69], s[80:81]
	s_mov_b64 s[74:75], s[86:87]
	v_writelane_b32 v254, s57, 48
	v_writelane_b32 v254, s95, 49
	v_writelane_b32 v254, s68, 27
	s_ashr_i32 s0, s2, 8
	s_ashr_i32 s1, s0, 31
	v_writelane_b32 v254, s69, 28
	s_lshl_b32 s3, s2, 17
	v_writelane_b32 v254, s70, 29
	s_lshl_b64 s[0:1], s[0:1], 23
	s_and_b32 s3, s3, 0x7e0000
	v_writelane_b32 v254, s71, 30
	s_or_b32 s0, s0, s3
	v_writelane_b32 v254, s72, 31
	s_add_u32 s3, s78, s0
	v_writelane_b32 v254, s73, 32
	s_addc_u32 s5, s79, s1
	s_lshl_b32 s4, s2, 2
	v_writelane_b32 v254, s74, 33
	s_and_b32 s6, s4, 0x300
	v_writelane_b32 v254, s75, 34
	s_add_u32 s4, s3, s6
	s_addc_u32 s5, s5, 0
	v_readlane_b32 s3, v254, 39
	v_lshlrev_b32_e32 v11, 3, v220
	v_lshrrev_b32_e32 v12, 4, v220
	v_lshlrev_b32_e32 v8, 5, v220
	s_add_u32 s0, s3, s0
	v_readlane_b32 s3, v254, 40
	v_and_b32_e32 v128, 0x78, v11
	v_lshlrev_b32_e32 v32, 9, v12
	v_add_u32_e32 v4, 0x4000, v8
	v_add_u32_e32 v8, 0xc000, v8
	s_addc_u32 s1, s3, s1
	v_mov_b32_e32 v131, 0
	v_lshlrev_b32_e32 v130, 1, v128
	v_and_b32_e32 v4, 0xfe00, v4
	v_or_b32_e32 v34, 0x8000, v32
	v_and_b32_e32 v8, 0x1fe00, v8
	s_add_u32 s0, s0, s6
	v_lshl_add_u64 v[0:1], s[4:5], 0, v[130:131]
	v_lshlrev_b32_e32 v2, 10, v12
	v_mov_b32_e32 v3, v131
	v_lshlrev_b32_e32 v4, 1, v4
	v_mov_b32_e32 v5, v131
	v_lshlrev_b32_e32 v6, 1, v34
	v_mov_b32_e32 v7, v131
	v_lshlrev_b32_e32 v8, 1, v8
	v_mov_b32_e32 v9, v131
	s_addc_u32 s1, s1, 0
	v_lshl_add_u64 v[42:43], v[0:1], 0, v[2:3]
	v_lshl_add_u64 v[44:45], v[0:1], 0, v[4:5]
	v_lshl_add_u64 v[46:47], v[0:1], 0, v[6:7]
	v_lshl_add_u64 v[48:49], v[0:1], 0, v[8:9]
	v_lshl_add_u64 v[0:1], s[0:1], 0, v[130:131]
	v_add_u32_e32 v33, 0x200, v220
	v_lshl_add_u64 v[50:51], v[0:1], 0, v[2:3]
	v_lshl_add_u64 v[52:53], v[0:1], 0, v[4:5]
	v_lshl_add_u64 v[54:55], v[0:1], 0, v[6:7]
	v_lshl_add_u64 v[56:57], v[0:1], 0, v[8:9]
	v_and_b32_e32 v0, 0xf0, v144
	s_movk_i32 s0, 0x110
	v_lshrrev_b32_e32 v1, 4, v33
	v_lshl_or_b32 v132, s94, 4, v145
	s_add_i32 s1, 0, 0x11000
	v_mul_u32_u24_e32 v187, 0x110, v1
	v_lshlrev_b32_e32 v38, 9, v1
	v_mul_lo_u32 v1, v132, s0
	v_add_u32_e32 v195, s1, v0
	s_add_i32 s1, 0, 0x19800
	v_add_u32_e32 v190, 0, v1
	v_or_b32_e32 v1, 48, v221
	s_cmp_lg_u32 0, -1
	v_mul_u32_u24_e32 v193, 0x110, v1
	v_or_b32_e32 v1, 0x70, v221
	s_cselect_b32 s3, 0, 0
	v_mul_u32_u24_e32 v194, 0x110, v1
	v_and_b32_e32 v1, 24, v11
	s_add_i32 s3, s3, 0x11000
	v_add_u32_e32 v129, 0, v0
	v_add_u32_e32 v35, 0x600, v220
	v_add_u32_e32 v196, s1, v0
	v_or_b32_e32 v0, v146, v147
	v_add_u32_e32 v1, s3, v1
	v_lshrrev_b32_e32 v10, 4, v221
	v_lshrrev_b32_e32 v2, 4, v35
	v_mad_u32_u24 v197, v0, s0, v1
	v_add_u32_e32 v0, 1, v132
	v_mul_u32_u24_e32 v186, 0x110, v12
	v_mul_u32_u24_e32 v188, 0x110, v2
	v_lshlrev_b32_e32 v36, 9, v2
	v_lshlrev_b32_e32 v40, 2, v10
	v_lshlrev_b32_e32 v37, 3, v10
	v_cvt_f32_i32_e32 v202, v0
	global_load_dwordx4 v[0:3], v[42:43], off nt
	global_load_dwordx4 v[4:7], v[44:45], off nt
	global_load_dwordx4 v[8:11], v[46:47], off nt
	global_load_dwordx4 v[12:15], v[48:49], off nt
	global_load_dwordx4 v[16:19], v[50:51], off nt
	global_load_dwordx4 v[20:23], v[52:53], off nt
	global_load_dwordx4 v[24:27], v[54:55], off nt
	global_load_dwordx4 v[28:31], v[56:57], off nt
	v_writelane_b32 v254, s94, 50
	v_sub_u32_e32 v39, v132, v40
	v_readlane_b32 s4, v254, 3
	v_cvt_f32_i32_e32 v203, v39
	v_xad_u32 v39, v40, -1, v132
	v_readlane_b32 s8, v254, 7
	v_readlane_b32 s9, v254, 8
	v_cvt_f32_i32_e32 v204, v39
	v_or_b32_e32 v39, 3, v40
	v_cmp_lt_i32_e64 s[8:9], v132, v39
	v_sub_u32_e32 v39, v132, v39
	v_and_b32_e32 v130, 48, v221
	v_readlane_b32 s12, v254, 11
	v_readlane_b32 s13, v254, 12
	v_cvt_f32_i32_e32 v206, v39
	v_or_b32_e32 v39, 17, v40
	v_lshl_add_u64 v[134:135], s[12:13], 0, v[130:131]
	v_cmp_lt_i32_e64 s[12:13], v132, v39
	v_sub_u32_e32 v39, v132, v39
	v_readlane_b32 s16, v254, 15
	v_readlane_b32 s17, v254, 16
	v_cvt_f32_i32_e32 v208, v39
	v_or_b32_e32 v39, 19, v40
	v_cmp_lt_i32_e64 s[16:17], v132, v39
	v_sub_u32_e32 v39, v132, v39
	v_cvt_f32_i32_e32 v210, v39
	v_or_b32_e32 v39, 33, v40
	v_cmp_lt_i32_e64 s[20:21], v132, v39
	v_sub_u32_e32 v39, v132, v39
	v_cvt_f32_i32_e32 v212, v39
	v_or_b32_e32 v39, 35, v40
	v_cmp_lt_i32_e64 s[24:25], v132, v39
	v_sub_u32_e32 v39, v132, v39
	v_or_b32_e32 v41, 2, v40
	v_cvt_f32_i32_e32 v214, v39
	v_or_b32_e32 v39, 49, v40
	v_sub_u32_e32 v42, v132, v41
	v_cmp_lt_i32_e64 s[28:29], v132, v39
	v_sub_u32_e32 v39, v132, v39
	v_readlane_b32 s10, v254, 9
	v_readlane_b32 s11, v254, 10
	v_cvt_f32_i32_e32 v205, v42
	v_or_b32_e32 v42, 16, v40
	v_cvt_f32_i32_e32 v216, v39
	v_or_b32_e32 v39, 51, v40
	v_cmp_lt_i32_e64 s[10:11], v132, v41
	v_sub_u32_e32 v41, v132, v42
	v_cmp_lt_i32_e64 s[34:35], v132, v39
	v_sub_u32_e32 v39, v132, v39
	v_readlane_b32 s18, v254, 17
	v_readlane_b32 s19, v254, 18
	v_cvt_f32_i32_e32 v207, v41
	v_or_b32_e32 v41, 18, v40
	v_or_b32_e32 v44, 32, v40
	v_cvt_f32_i32_e32 v218, v39
	v_or_b32_e32 v39, 0x41, v40
	v_sub_u32_e32 v43, v132, v41
	v_cmp_lt_i32_e64 s[18:19], v132, v41
	v_sub_u32_e32 v41, v132, v44
	v_cmp_lt_i32_e64 s[38:39], v132, v39
	v_sub_u32_e32 v39, v132, v39
	v_cvt_f32_i32_e32 v211, v41
	v_or_b32_e32 v41, 34, v40
	v_or_b32_e32 v46, 48, v40
	v_cvt_f32_i32_e32 v222, v39
	v_or_b32_e32 v39, 0x43, v40
	v_cvt_f32_i32_e32 v209, v43
	v_sub_u32_e32 v43, v132, v41
	v_cmp_lt_i32_e64 s[26:27], v132, v41
	v_sub_u32_e32 v41, v132, v46
	v_cmp_lt_i32_e64 s[42:43], v132, v39
	v_sub_u32_e32 v39, v132, v39
	v_cvt_f32_i32_e32 v215, v41
	v_or_b32_e32 v41, 50, v40
	v_or_b32_e32 v48, 64, v40
	v_cvt_f32_i32_e32 v224, v39
	v_or_b32_e32 v39, 0x51, v40
	v_cvt_f32_i32_e32 v213, v43
	v_sub_u32_e32 v43, v132, v41
	v_cmp_lt_i32_e64 s[36:37], v132, v41
	v_sub_u32_e32 v41, v132, v48
	v_cmp_lt_i32_e64 s[46:47], v132, v39
	v_sub_u32_e32 v39, v132, v39
	v_cvt_f32_i32_e32 v219, v41
	v_or_b32_e32 v41, 0x42, v40
	v_or_b32_e32 v50, 0x50, v40
	v_cvt_f32_i32_e32 v226, v39
	v_or_b32_e32 v39, 0x53, v40
	v_cvt_f32_i32_e32 v217, v43
	v_sub_u32_e32 v43, v132, v41
	v_cmp_lt_i32_e64 s[44:45], v132, v41
	v_sub_u32_e32 v41, v132, v50
	v_cmp_lt_i32_e64 s[50:51], v132, v39
	v_sub_u32_e32 v39, v132, v39
	v_cvt_f32_i32_e32 v225, v41
	v_or_b32_e32 v41, 0x52, v40
	v_cvt_f32_i32_e32 v228, v39
	v_or_b32_e32 v39, 0x61, v40
	v_or_b32_e32 v52, 0x60, v40
	v_cvt_f32_i32_e32 v223, v43
	v_sub_u32_e32 v43, v132, v41
	v_cmp_lt_i32_e64 s[52:53], v132, v41
	v_sub_u32_e32 v41, v132, v52
	v_cmp_lt_i32_e64 s[54:55], v132, v39
	v_sub_u32_e32 v39, v132, v39
	v_cvt_f32_i32_e32 v229, v41
	v_cvt_f32_i32_e32 v230, v39
	v_or_b32_e32 v39, 0x63, v40
	v_or_b32_e32 v41, 0x62, v40
	v_cvt_f32_i32_e32 v227, v43
	v_sub_u32_e32 v43, v132, v41
	v_cmp_lt_i32_e64 s[58:59], v132, v39
	v_sub_u32_e32 v39, v132, v39
	v_or_b32_e32 v54, 0x70, v40
	v_and_b32_e32 v189, 48, v220
	v_cvt_f32_i32_e32 v231, v43
	v_cvt_f32_i32_e32 v232, v39
	v_or_b32_e32 v39, 0x71, v40
	v_sub_u32_e32 v43, v132, v54
	s_add_i32 s0, s2, s92
	s_ashr_i32 s3, s2, 31
	v_add_u32_e32 v201, s1, v189
	v_cvt_f32_i32_e32 v233, v43
	v_sub_u32_e32 v43, v132, v39
	v_or_b32_e32 v45, 0x72, v40
	s_lshl_b32 s71, s0, 16
	s_lshl_b32 s78, s92, 16
	s_lshl_b32 s79, s0, 1
	s_lshl_b32 s33, s92, 1
	s_lshl_b64 s[0:1], s[2:3], 15
	v_cvt_f32_i32_e32 v234, v43
	v_or_b32_e32 v43, 0x73, v40
	v_sub_u32_e32 v47, v132, v45
	v_lshlrev_b32_e32 v35, 4, v35
	s_add_u32 s0, s88, s0
	v_cvt_f32_i32_e32 v235, v47
	v_sub_u32_e32 v47, v132, v43
	v_and_b32_e32 v130, 0xff00, v35
	s_addc_u32 s1, s89, s1
	v_cvt_f32_i32_e32 v236, v47
	v_lshl_add_u64 v[56:57], s[0:1], 0, v[130:131]
	v_and_b32_e32 v130, 0x3f00, v144
	v_lshlrev_b32_e32 v33, 4, v33
	s_mov_b64 s[60:61], 0x17800000
	v_lshl_add_u64 v[140:141], s[0:1], 0, v[130:131]
	v_and_b32_e32 v130, 0x7f00, v33
	v_readlane_b32 s5, v254, 4
	v_readlane_b32 s6, v254, 5
	v_readlane_b32 s7, v254, 6
	v_readlane_b32 s14, v254, 13
	v_readlane_b32 s15, v254, 14
	v_lshl_add_u64 v[138:139], v[56:57], 0, s[60:61]
	s_ashr_i32 s63, s92, 31
	s_mov_b32 s62, s92
	v_lshl_add_u64 v[56:57], s[0:1], 0, v[130:131]
	v_lshlrev_b32_e32 v144, 1, v32
	v_mbcnt_lo_u32_b32 v32, -1, 0
	s_mov_b32 s87, 0
	v_add_u32_e32 v191, 0, v189
	v_mul_u32_u24_e32 v192, 0x110, v145
	v_add_u32_e32 v198, 0x2200, v197
	v_add_u32_e32 v199, 0x4400, v197
	v_add_u32_e32 v200, 0x6600, v197
	v_ashrrev_i32_e32 v133, 31, v132
	v_cmp_lt_i32_e64 s[4:5], v132, v40
	v_cmp_gt_i32_e64 s[6:7], v132, v40
	v_cmp_lt_i32_e64 s[14:15], v132, v42
	v_cmp_lt_i32_e64 s[22:23], v132, v44
	v_cmp_lt_i32_e64 s[30:31], v132, v46
	v_cmp_lt_i32_e64 s[40:41], v132, v48
	v_cmp_lt_i32_e64 s[48:49], v132, v50
	v_cmp_lt_i32_e64 s[56:57], v132, v52
	v_lshlrev_b32_e32 v136, 4, v145
	v_mov_b32_e32 v137, v131
	s_lshl_b64 s[80:81], s[62:63], 15
	v_lshl_add_u64 v[142:143], v[56:57], 0, s[60:61]
	s_lshl_b32 s3, s2, 7
	s_mov_b64 s[94:95], s[92:93]
	s_lshl_b32 s70, s92, 7
	v_mov_b32_e32 v237, 0xc0a00000
	s_mov_b32 s92, 0xc2fc0000
	v_lshlrev_b32_e32 v146, 1, v38
	v_lshlrev_b32_e32 v148, 1, v34
	v_lshlrev_b32_e32 v150, 1, v36
	s_mov_b32 s93, 0x5040100
	v_add_u32_e32 v238, v190, v37
	v_mbcnt_hi_u32_b32 v239, -1, v32
	v_lshlrev_b32_e32 v152, 1, v40
	v_lshlrev_b32_e32 v154, 1, v42
	v_lshlrev_b32_e32 v156, 1, v44
	v_lshlrev_b32_e32 v158, 1, v46
	v_lshlrev_b32_e32 v160, 1, v48
	v_lshlrev_b32_e32 v162, 1, v50
	v_lshlrev_b32_e32 v164, 1, v52
	v_mov_b32_e32 v240, 0x260
	v_lshlrev_b32_e32 v166, 1, v54
	v_mov_b32_e32 v241, 0x42800000
	v_mov_b32_e32 v242, 0x42000000
	v_not_b32_e32 v243, 63
	s_mov_b32 s74, s2
	v_cmp_lt_i32_e64 s[60:61], v132, v41
	v_cmp_lt_i32_e64 s[62:63], v132, v39
	v_cmp_lt_i32_e64 s[64:65], v132, v54
	v_cmp_lt_i32_e64 s[66:67], v132, v43
	v_cmp_lt_i32_e64 s[68:69], v132, v45
	s_waitcnt vmcnt(0)
	s_branch .LBB0_578

.LBB0_578:
	s_bfe_u32 s72, s74, 0x20006
	v_cvt_f32_ubyte0_e32 v32, s72
	v_fmamk_f32 v32, v32, 0xbfaaaaab, v237
	v_cmp_gt_f32_e32 vcc, s92, v32
	s_ashr_i32 s0, s74, 8
	s_and_b64 s[96:97], vcc, exec
	v_cndmask_b32_e32 v33, 0, v241, vcc
	v_add_f32_e32 v32, v32, v33
	v_exp_f32_e32 v32, v32
	s_cselect_b32 s1, 0xffffffc0, 0
	s_and_b32 s73, s3, 0x1f80
	v_readlane_b32 s75, v254, 42
	v_ldexp_f32 v32, v32, s1
	s_ashr_i32 s1, s0, 31
	s_lshl_b64 s[0:1], s[0:1], 13
	s_or_b32 s0, s0, s73
	s_lshl_b64 s[96:97], s[0:1], 10
	s_add_u32 s73, s77, s96
	s_addc_u32 s76, s75, s97
	s_lshl_b32 s75, s72, 7
	s_lshl_b32 s72, s72, 8
	s_add_u32 s96, s73, s72
	s_addc_u32 s97, s76, 0
	v_lshlrev_b32_e32 v130, 1, v128
	v_sub_f32_e32 v64, 1.0, v32
	v_add_u32_e32 v32, v129, v186
	v_add_u32_e32 v33, v129, v187
	v_add_u32_e32 v34, v129, v188
	v_lshl_add_u64 v[44:45], s[96:97], 0, v[130:131]
	v_mov_b32_e32 v145, v131
	s_waitcnt vmcnt(8)
	ds_write_b128 v32, v[0:3]
	ds_write_b128 v33, v[4:7]
	ds_write_b128 v32, v[8:11] offset:17408
	ds_write_b128 v34, v[12:15]
	ds_write_b128 v32, v[16:19] offset:34816
	ds_write_b128 v33, v[20:23] offset:34816
	ds_write_b128 v32, v[24:27] offset:52224
	ds_write_b128 v34, v[28:31] offset:34816
	v_lshl_add_u64 v[32:33], v[44:45], 0, v[144:145]
	v_mov_b32_e32 v147, v131
	v_lshl_add_u64 v[56:57], v[140:141], 0, v[136:137]
	s_mov_b32 s72, 0x17800000
	global_load_dwordx4 v[32:35], v[32:33], off nt
	v_lshl_add_u64 v[36:37], v[44:45], 0, v[146:147]
	v_mov_b32_e32 v149, v131
	v_mov_b32_e32 v151, v131
	v_add_co_u32_e32 v48, vcc, s72, v56
	global_load_dwordx4 v[36:39], v[36:37], off nt
	v_lshl_add_u64 v[40:41], v[44:45], 0, v[148:149]
	v_lshl_add_u64 v[44:45], v[44:45], 0, v[150:151]
	v_addc_co_u32_e32 v49, vcc, 0, v57, vcc
	s_mov_b32 s72, 0x17804000
	global_load_dwordx4 v[40:43], v[40:41], off nt
	v_lshl_add_u64 v[52:53], v[142:143], 0, v[136:137]
	global_load_dwordx4 v[44:47], v[44:45], off nt
	v_add_co_u32_e32 v56, vcc, s72, v56
	global_load_dwordx4 v[48:51], v[48:49], off nt
	s_nop 0
	v_addc_co_u32_e32 v57, vcc, 0, v57, vcc
	global_load_dwordx4 v[52:55], v[52:53], off nt
	v_lshl_add_u64 v[60:61], v[138:139], 0, v[136:137]
	global_load_dwordx4 v[56:59], v[56:57], off nt
	s_mov_b32 s72, 0x800000
	global_load_dwordx4 v[60:63], v[60:61], off nt
	v_cmp_gt_f32_e32 vcc, s72, v64
	s_and_b64 s[96:97], vcc, exec
	s_cselect_b32 s72, 32, 0
	v_add_u32_e32 v100, v190, v189
	v_add_u32_e32 v98, v191, v192
	v_add_u32_e32 v99, v191, v193
	v_add_u32_e32 v101, v191, v194
	s_waitcnt lgkmcnt(0)
	s_barrier
	v_ldexp_f32 v96, v64, s72
	ds_read_b128 v[64:67], v100
	ds_read_b128 v[68:71], v98 offset:34816
	ds_read_b128 v[72:75], v98 offset:39168
	ds_read_b128 v[76:79], v98 offset:43520
	ds_read_b128 v[80:83], v99 offset:34816
	ds_read_b128 v[84:87], v98 offset:52224
	ds_read_b128 v[88:91], v98 offset:56576
	ds_read_b128 v[92:95], v98 offset:60928
	ds_read_b128 v[102:105], v101 offset:34816
	s_waitcnt lgkmcnt(7)
	v_mfma_f32_16x16x32_bf16 v[68:71], v[68:71], v[64:67], 0
	s_add_i32 s74, s74, s94
	s_cmpk_gt_i32 s74, 0x3ff
	s_cselect_b64 s[96:97], -1, 0
	s_waitcnt lgkmcnt(6)
	v_mfma_f32_16x16x32_bf16 v[72:75], v[72:75], v[64:67], 0
	v_cndmask_b32_e32 v97, 0, v242, vcc
	s_and_b64 vcc, exec, s[96:97]
	s_waitcnt lgkmcnt(5)
	v_mfma_f32_16x16x32_bf16 v[76:79], v[76:79], v[64:67], 0
	s_waitcnt lgkmcnt(4)
	v_mfma_f32_16x16x32_bf16 v[80:83], v[80:83], v[64:67], 0
	s_waitcnt lgkmcnt(3)
	v_mfma_f32_16x16x32_bf16 v[84:87], v[84:87], v[64:67], 0
	s_waitcnt lgkmcnt(2)
	v_mfma_f32_16x16x32_bf16 v[88:91], v[88:91], v[64:67], 0
	s_waitcnt lgkmcnt(1)
	v_mfma_f32_16x16x32_bf16 v[92:95], v[92:95], v[64:67], 0
	s_waitcnt lgkmcnt(0)
	v_mfma_f32_16x16x32_bf16 v[64:67], v[102:105], v[64:67], 0
	ds_read_b128 v[102:105], v100 offset:64
	ds_read_b128 v[106:109], v98 offset:34880
	ds_read_b128 v[110:113], v98 offset:39232
	ds_read_b128 v[114:117], v98 offset:43584
	ds_read_b128 v[118:121], v99 offset:34880
	ds_read_b128 v[122:125], v98 offset:52288
	ds_read_b128 v[168:171], v98 offset:56640
	ds_read_b128 v[172:175], v98 offset:60992
	ds_read_b128 v[176:179], v101 offset:34880
	s_waitcnt lgkmcnt(7)
	v_mfma_f32_16x16x32_bf16 v[68:71], v[106:109], v[102:105], v[68:71]
	s_waitcnt lgkmcnt(6)
	v_mfma_f32_16x16x32_bf16 v[72:75], v[110:113], v[102:105], v[72:75]
	s_waitcnt lgkmcnt(5)
	v_mfma_f32_16x16x32_bf16 v[76:79], v[114:117], v[102:105], v[76:79]
	s_waitcnt lgkmcnt(4)
	v_mfma_f32_16x16x32_bf16 v[80:83], v[118:121], v[102:105], v[80:83]
	s_waitcnt lgkmcnt(3)
	v_mfma_f32_16x16x32_bf16 v[84:87], v[122:125], v[102:105], v[84:87]
	s_waitcnt lgkmcnt(2)
	v_mfma_f32_16x16x32_bf16 v[88:91], v[168:171], v[102:105], v[88:91]
	s_waitcnt lgkmcnt(1)
	v_mfma_f32_16x16x32_bf16 v[92:95], v[172:175], v[102:105], v[92:95]
	s_waitcnt lgkmcnt(0)
	v_mfma_f32_16x16x32_bf16 v[64:67], v[176:179], v[102:105], v[64:67]
	ds_read_b128 v[102:105], v100 offset:128
	ds_read_b128 v[106:109], v98 offset:34944
	ds_read_b128 v[110:113], v98 offset:39296
	ds_read_b128 v[114:117], v98 offset:43648
	ds_read_b128 v[118:121], v99 offset:34944
	ds_read_b128 v[122:125], v98 offset:52352
	ds_read_b128 v[168:171], v98 offset:56704
	ds_read_b128 v[172:175], v98 offset:61056
	ds_read_b128 v[176:179], v101 offset:34944
	s_waitcnt lgkmcnt(7)
	v_mfma_f32_16x16x32_bf16 v[68:71], v[106:109], v[102:105], v[68:71]
	s_waitcnt lgkmcnt(6)
	v_mfma_f32_16x16x32_bf16 v[72:75], v[110:113], v[102:105], v[72:75]
	s_waitcnt lgkmcnt(5)
	v_mfma_f32_16x16x32_bf16 v[76:79], v[114:117], v[102:105], v[76:79]
	s_waitcnt lgkmcnt(4)
	v_mfma_f32_16x16x32_bf16 v[80:83], v[118:121], v[102:105], v[80:83]
	s_waitcnt lgkmcnt(3)
	v_mfma_f32_16x16x32_bf16 v[106:109], v[122:125], v[102:105], v[84:87]
	s_waitcnt lgkmcnt(2)
	v_mfma_f32_16x16x32_bf16 v[110:113], v[168:171], v[102:105], v[88:91]
	s_waitcnt lgkmcnt(1)
	v_mfma_f32_16x16x32_bf16 v[114:117], v[172:175], v[102:105], v[92:95]
	s_waitcnt lgkmcnt(0)
	v_mfma_f32_16x16x32_bf16 v[64:67], v[176:179], v[102:105], v[64:67]
	ds_read_b128 v[102:105], v100 offset:192
	ds_read_b128 v[84:87], v98 offset:35008
	ds_read_b128 v[88:91], v98 offset:39360
	ds_read_b128 v[118:121], v98 offset:43712
	ds_read_b128 v[122:125], v99 offset:35008
	ds_read_b128 v[168:171], v98 offset:52416
	ds_read_b128 v[172:175], v98 offset:56768
	ds_read_b128 v[176:179], v98 offset:61120
	ds_read_b128 v[180:183], v101 offset:35008
	v_add_u32_e32 v98, v195, v186
	s_waitcnt vmcnt(7)
	ds_write_b128 v98, v[32:35]
	s_waitcnt lgkmcnt(8)
	v_mfma_f32_16x16x32_bf16 v[92:95], v[84:87], v[102:105], v[68:71]
	v_add_u32_e32 v32, v195, v187
	s_waitcnt vmcnt(6)
	ds_write_b128 v32, v[36:39]
	s_waitcnt vmcnt(5)
	ds_write_b128 v98, v[40:43] offset:17408
	v_add_u32_e32 v32, v195, v188
	s_waitcnt lgkmcnt(9)
	v_mfma_f32_16x16x32_bf16 v[88:91], v[88:91], v[102:105], v[72:75]
	s_waitcnt vmcnt(4)
	ds_write_b128 v32, v[44:47]
	v_add_u32_e32 v32, v196, v186
	v_add_u32_e32 v33, v196, v187
	s_waitcnt lgkmcnt(9)
	v_mfma_f32_16x16x32_bf16 v[84:87], v[118:121], v[102:105], v[76:79]
	s_waitcnt vmcnt(3)
	ds_write_b128 v32, v[48:51]
	s_waitcnt vmcnt(2)
	ds_write_b128 v33, v[52:55]
	s_waitcnt vmcnt(1)
	ds_write_b128 v32, v[56:59] offset:17408
	v_add_u32_e32 v32, v196, v188
	s_waitcnt lgkmcnt(11)
	v_mfma_f32_16x16x32_bf16 v[80:83], v[122:125], v[102:105], v[80:83]
	s_waitcnt vmcnt(0)
	ds_write_b128 v32, v[60:63]
	s_waitcnt lgkmcnt(0)
	s_barrier
	v_mfma_f32_16x16x32_bf16 v[76:79], v[168:171], v[102:105], v[106:109]
	v_mfma_f32_16x16x32_bf16 v[72:75], v[172:175], v[102:105], v[110:113]
	v_mfma_f32_16x16x32_bf16 v[68:71], v[176:179], v[102:105], v[114:117]
	v_mfma_f32_16x16x32_bf16 v[64:67], v[180:183], v[102:105], v[64:67]
	s_cbranch_vccnz .LBB0_577
	s_ashr_i32 vcc_lo, s74, 8
	s_ashr_i32 vcc_hi, vcc_lo, 31
	s_and_b32 s72, s71, 0x3f0000
	s_lshl_b64 vcc, vcc, 23
	s_lshl_b32 s72, s72, 1
	s_or_b32 s76, vcc_lo, s72
	v_readlane_b32 s72, v254, 45
	v_readlane_b32 s73, v254, 46
	s_add_u32 s72, s72, s76
	s_addc_u32 s73, s73, vcc_hi
	s_and_b32 s77, s79, 0x180
	s_lshl_b32 s77, s77, 1
	s_add_u32 s72, s72, s77
	s_addc_u32 s73, s73, 0
	v_lshl_add_u64 v[8:9], s[72:73], 0, v[130:131]
	v_readlane_b32 s72, v254, 39
	s_add_u32 s72, s72, s76
	v_readlane_b32 s73, v254, 40
	s_addc_u32 s73, s73, vcc_hi
	s_add_u32 s72, s72, s77
	s_addc_u32 s73, s73, 0
	v_lshl_add_u64 v[24:25], s[72:73], 0, v[130:131]
	v_lshl_add_u64 v[0:1], v[8:9], 0, v[144:145]
	v_lshl_add_u64 v[4:5], v[8:9], 0, v[146:147]
	v_lshl_add_u64 v[10:11], v[8:9], 0, v[148:149]
	v_lshl_add_u64 v[12:13], v[8:9], 0, v[150:151]
	v_lshl_add_u64 v[16:17], v[24:25], 0, v[144:145]
	v_lshl_add_u64 v[20:21], v[24:25], 0, v[146:147]
	v_lshl_add_u64 v[26:27], v[24:25], 0, v[148:149]
	v_lshl_add_u64 v[28:29], v[24:25], 0, v[150:151]
	global_load_dwordx4 v[0:3], v[0:1], off nt
	s_nop 0
	global_load_dwordx4 v[4:7], v[4:5], off nt
	s_nop 0
	global_load_dwordx4 v[8:11], v[10:11], off nt
	s_nop 0
	global_load_dwordx4 v[12:15], v[12:13], off nt
	s_nop 0
	global_load_dwordx4 v[16:19], v[16:17], off nt
	s_nop 0
	global_load_dwordx4 v[20:23], v[20:21], off nt
	s_nop 0
	global_load_dwordx4 v[24:27], v[26:27], off nt
	s_nop 0
	global_load_dwordx4 v[28:31], v[28:29], off nt
	v_readlane_b32 s77, v254, 41
	s_branch .LBB0_577
